# grid barrier v2: hand-written thread-0 protocol (returning local arrival, leader L2 writeback + non-returning cross-XCD add, every workgroup polls the cross-XCD counter; generation kept in an LDS word
# baseline (speedup 1.0000x reference)
; __device__ __forceinline__ unsigned xb_ld(unsigned* p)              { return __hip_atomic_load(p, __ATOMIC_RELAXED, __HIP_MEMORY_SCOPE_AGENT); }
; __device__ __forceinline__ unsigned xb_add(unsigned* p, unsigned v) { return __hip_atomic_fetch_add(p, v, __ATOMIC_RELAXED, __HIP_MEMORY_SCOPE_AGENT); }
; #define XB_SPIN(cond, bar) do { unsigned _sp = 0; while (cond) { __builtin_amdgcn_s_sleep(1); \
;     if ((++_sp & 255u) == 0u) { if (xb_ld(&(bar)[XB_TMO])) break; if (_sp > XB_SPIN_CAP) { atomicAdd(&(bar)[XB_TMO], 1u); break; } } } } while (0)
; __device__ __forceinline__ void xcd_barrier(const XcdBarrier& b) {
;     ...
;     if (threadIdx.x == 0) {
;         unsigned* bar = b.bar;
;         __builtin_amdgcn_s_waitcnt(0);
;         unsigned nloc = b.st[0], nx = b.st[1];
;         if (nloc == 0u) { xcd_barrier_complete(bar, b.x, nloc, nx); b.st[0] = nloc; b.st[1] = nx; }
;         const unsigned old = xb_add(&bar[XB_XSUB(b.x)], 1u);
;         const unsigned gen = old / nloc;
;         if (old + 1u == (gen + 1u) * nloc) {
;             __builtin_amdgcn_fence(__ATOMIC_RELEASE, "agent");
;             asm volatile("s_waitcnt vmcnt(0)" ::: "memory");
;             const unsigned og = xb_add(&bar[XB_TOP], 1u);
;             const unsigned tg = og / nx;
;             if (og + 1u == (tg + 1u) * nx) xb_add(&bar[XB_TOPGEN], 1u);
;             else XB_SPIN(xb_ld(&bar[XB_TOPGEN]) == tg, bar);
;             __builtin_amdgcn_fence(__ATOMIC_ACQUIRE, "agent");
;             xb_add(&bar[XB_XGEN(b.x)], 1u);
;             asm volatile("s_waitcnt vmcnt(0)" ::: "memory");
;         } else {
;             XB_SPIN(xb_ld(&bar[XB_XGEN(b.x)]) == gen, bar);
;             __builtin_amdgcn_fence(__ATOMIC_ACQUIRE, "agent");
;             asm volatile("s_waitcnt vmcnt(0)" ::: "memory");
;         }
.LBB0_89:
	s_waitcnt lgkmcnt(0)
	v_mov_b32_e32 v1, 0x20028
	ds_read_b32 v3, v1
	s_lshl_b32 s98, s93, 8
	s_add_u32 s98, s96, s98
	s_addc_u32 s99, s97, 0
	v_mov_b32_e32 v4, 0x1000
	v_mov_b32_e32 v5, 1
	global_atomic_add v4, v4, v5, s[98:99] offset:1024 sc0
	s_waitcnt vmcnt(0) lgkmcnt(0)
	v_add_u32_e32 v5, 1, v3
	ds_write_b32 v1, v5
	v_mul_lo_u32 v1, v5, v2
	v_add_u32_e32 v4, 1, v4
	v_mul_lo_u32 v5, v5, v0
	v_cmp_eq_u32_e32 vcc, v4, v1
	s_add_u32 s98, s26, 0x7400
	s_addc_u32 s99, s27, 0
	v_mov_b32_e32 v1, 0
	s_cbranch_vccz .Lnb0_poll
	buffer_wbl2 sc1
	s_waitcnt vmcnt(0)
	v_mov_b32_e32 v4, 1
	global_atomic_add v1, v4, s[98:99]
.Lnb0_poll:
	s_mov_b32 s100, 0
.Lnb0_loop:
	global_load_dword v4, v1, s[98:99] sc1
	s_waitcnt vmcnt(0)
	v_cmp_ge_u32_e32 vcc, v4, v5
	s_cbranch_vccnz .Lnb0_done
	s_sleep 1
	s_add_i32 s100, s100, 1
	s_cmp_lt_u32 s100, 0x100000
	s_cbranch_scc1 .Lnb0_loop
	s_add_u32 s98, s26, 0x4200
	s_addc_u32 s99, s27, 0
	v_mov_b32_e32 v4, 1
	global_atomic_add v1, v4, s[98:99]
.Lnb0_done:
	buffer_inv sc1
	s_waitcnt vmcnt(0) lgkmcnt(0)

; __global__ void __launch_bounds__(512, 2) fwd_megakernel(Args a) {
	.amdhsa_kernel _Z14fwd_megakernel4Args
		.amdhsa_group_segment_fixed_size 0
		.amdhsa_private_segment_fixed_size 0
		.amdhsa_kernarg_size 448
		.amdhsa_user_sgpr_count 2
		.amdhsa_user_sgpr_dispatch_ptr 0
		.amdhsa_user_sgpr_queue_ptr 0
		.amdhsa_user_sgpr_kernarg_segment_ptr 1
		.amdhsa_user_sgpr_dispatch_id 0
		.amdhsa_user_sgpr_kernarg_preload_length 0
		.amdhsa_user_sgpr_kernarg_preload_offset 0
		.amdhsa_user_sgpr_private_segment_size 0
		.amdhsa_uses_dynamic_stack 0
		.amdhsa_enable_private_segment 0
		.amdhsa_system_sgpr_workgroup_id_x 1
		.amdhsa_system_sgpr_workgroup_id_y 0
		.amdhsa_system_sgpr_workgroup_id_z 0
		.amdhsa_system_sgpr_workgroup_info 0
		.amdhsa_system_vgpr_workitem_id 2
		.amdhsa_next_free_vgpr 252
		.amdhsa_next_free_sgpr 102
		.amdhsa_accum_offset 252
		.amdhsa_reserve_vcc 1
		.amdhsa_float_round_mode_32 0
		.amdhsa_float_round_mode_16_64 0
		.amdhsa_float_denorm_mode_32 3
		.amdhsa_float_denorm_mode_16_64 3
		.amdhsa_dx10_clamp 1
		.amdhsa_ieee_mode 1
		.amdhsa_fp16_overflow 0
		.amdhsa_tg_split 0
		.amdhsa_exception_fp_ieee_invalid_op 0
		.amdhsa_exception_fp_denorm_src 0
		.amdhsa_exception_fp_ieee_div_zero 0
		.amdhsa_exception_fp_ieee_overflow 0
		.amdhsa_exception_fp_ieee_underflow 0
		.amdhsa_exception_fp_ieee_inexact 0
		.amdhsa_exception_int_div_zero 0
	.end_amdhsa_kernel

; __global__ void __launch_bounds__(512, 2) fwd_megakernel(Args a) {
amdhsa.kernels:
  - .agpr_count:     0
    .args:
      - .offset:         0
        .size:           192
        .value_kind:     by_value
      - .offset:         192
        .size:           4
        .value_kind:     hidden_block_count_x
      - .offset:         196
        .size:           4
        .value_kind:     hidden_block_count_y
      - .offset:         200
        .size:           4
        .value_kind:     hidden_block_count_z
      - .offset:         204
        .size:           2
        .value_kind:     hidden_group_size_x
      - .offset:         206
        .size:           2
        .value_kind:     hidden_group_size_y
      - .offset:         208
        .size:           2
        .value_kind:     hidden_group_size_z
      - .offset:         210
        .size:           2
        .value_kind:     hidden_remainder_x
      - .offset:         212
        .size:           2
        .value_kind:     hidden_remainder_y
      - .offset:         214
        .size:           2
        .value_kind:     hidden_remainder_z
      - .offset:         232
        .size:           8
        .value_kind:     hidden_global_offset_x
      - .offset:         240
        .size:           8
        .value_kind:     hidden_global_offset_y
      - .offset:         248
        .size:           8
        .value_kind:     hidden_global_offset_z
      - .offset:         256
        .size:           2
        .value_kind:     hidden_grid_dims
      - .offset:         280
        .size:           8
        .value_kind:     hidden_multigrid_sync_arg
      - .offset:         312
        .size:           4
        .value_kind:     hidden_dynamic_lds_size
    .group_segment_fixed_size: 0
    .kernarg_segment_align: 8
    .kernarg_segment_size: 448
    .language:       OpenCL C
    .language_version:
      - 2
      - 0
    .max_flat_workgroup_size: 512
    .name:           _Z14fwd_megakernel4Args
    .private_segment_fixed_size: 0
    .sgpr_count:     108
    .sgpr_spill_count: 66
    .symbol:         _Z14fwd_megakernel4Args.kd
    .uniform_work_group_size: 1
    .uses_dynamic_stack: false
    .vgpr_count:     252
    .vgpr_spill_count: 0
    .wavefront_size: 64
